# attention item preamble: two second-tile loads issued ahead of the LDS-ready barrier
# speedup vs baseline: 1.0014x; 1.0014x over previous
; DEV void attn_item(const Params& p, int item, char* smem) {
;     ...
;   f32x16 o[2][2];
; #pragma unroll
;   for (int dt = 0; dt < 2; dt++)
; #pragma unroll
;     for (int jt = 0; jt < 2; jt++)
; #pragma unroll
;       for (int r = 0; r < 16; r++) o[dt][jt][r] = 0.f;
;   float mrun[2] = {-1e30f, -1e30f}, lrun[2] = {0.f, 0.f};
;   u32x4 rk0, rk1, rv0;
;   const int k0row = tid / 12, k0cc = tid - k0row * 12;
;   const int k1id = 256 + (tid & 127), k1row = k1id / 12, k1cc = k1id - k1row * 12;
;   const bool has_k1 = tid < 128;
;   const int vrow = tid >> 2, vcc = tid & 3;
;   const int ntile = nkeys >> 5;
;   __syncthreads();
;   rk0 = *(const u32x4*)(Kb + (size_t)k0row * 96 + k0cc * 8);
;   rk1 = *(const u32x4*)(Kb + (size_t)k1row * 96 + k1cc * 8);
;   rv0 = *(const u32x4*)(Vb + (size_t)vrow * 8448 + vcc * 8);
;   *(u32x4*)(Ks + k0row * ASTR + k0cc * 8) = rk0;
;   if (has_k1) *(u32x4*)(Ks + k1row * ASTR + k1cc * 8) = rk1;
;   *(uint2*)(Vs + vrow * VSTR + vcc * 8) = make_uint2(rv0[0], rv0[1]);
;   *(uint2*)(Vs + vrow * VSTR + vcc * 8 + 4) = make_uint2(rv0[2], rv0[3]);
;   __syncthreads();
;   if (ntile > 1) {
;     rk0 = *(const u32x4*)(Kb + (size_t)(32 + k0row) * 96 + k0cc * 8);
;     rk1 = *(const u32x4*)(Kb + (size_t)(32 + k1row) * 96 + k1cc * 8);
;     rv0 = *(const u32x4*)(Vb + (size_t)vrow * 8448 + 32 + vcc * 8);
;   }
.LBB0_751:
	s_or_b64 exec, exec, s[14:15]
	s_movk_i32 s15, 0x58
	v_mul_lo_u32 v15, v12, s15
	v_lshl_add_u32 v186, v14, 1, v15
	v_add_u32_e32 v14, 0x3400, v186
	s_waitcnt vmcnt(0)
	ds_write2_b64 v14, v[2:3], v[4:5] offset1:1
	v_lshlrev_b64 v[2:3], 1, v[174:175]
	v_lshl_add_u64 v[4:5], v[8:9], 0, v[2:3]
	s_movk_i32 s14, 0x1000
	v_add_co_u32_e32 v4, vcc, s14, v4
	s_waitcnt lgkmcnt(0)
	s_nop 0
	v_addc_co_u32_e32 v5, vcc, 0, v5, vcc
	global_load_dwordx4 v[160:163], v[6:7], off offset:64
	global_load_dwordx4 v[164:167], v[4:5], off offset:2048
	s_barrier
	v_add_u32_e32 v6, 32, v11
	v_mov_b64_e32 v[4:5], s[12:13]
	s_movk_i32 s14, 0xc0
	v_mad_i64_i32 v[4:5], s[12:13], v6, s14, v[4:5]
	v_lshlrev_b64 v[6:7], 1, v[176:177]
	v_lshl_add_u64 v[4:5], v[4:5], 0, v[6:7]
	global_load_dwordx4 v[168:171], v[4:5], off
	v_mad_i64_i32 v[4:5], s[12:13], v11, s14, 0
	s_movk_i32 s12, 0x4200
	s_nop 0
	v_mad_i64_i32 v[8:9], s[12:13], v12, s12, 0
	v_and_b32_e32 v173, 31, v172
	s_movk_i32 s13, 0xd0
	v_mad_u32_u24 v187, v173, s13, v0
	v_lshlrev_b32_e32 v0, 3, v10
	v_mad_u32_u24 v177, v173, s15, v0
	v_and_b32_e32 v0, 3, v172
	v_lshl_add_u64 v[8:9], s[10:11], 0, v[8:9]
	v_lshlrev_b32_e32 v0, 4, v0
	v_lshl_add_u64 v[8:9], v[8:9], 0, v[0:1]
	s_mov_b32 s10, 0x15555556
	v_lshl_add_u64 v[178:179], s[0:1], 0, v[8:9]
	v_mul_hi_u32 v0, v13, s10
	v_mov_b64_e32 v[8:9], s[8:9]
	v_mad_u64_u32 v[8:9], s[10:11], v0, s14, v[8:9]
	v_lshl_add_u64 v[2:3], v[8:9], 0, v[2:3]
	v_lshl_add_u64 v[180:181], s[2:3], 0, v[2:3]
	v_lshl_add_u64 v[2:3], s[8:9], 0, v[4:5]
	v_lshl_add_u64 v[2:3], v[2:3], 0, v[6:7]
	v_mov_b32_e32 v14, v1
	v_mov_b32_e32 v15, v1
	v_lshlrev_b32_e32 v189, 2, v10
	v_lshl_add_u64 v[182:183], s[2:3], 0, v[2:3]
	v_mov_b32_e32 v0, v1
	v_mov_b32_e32 v2, v1
	v_mov_b32_e32 v3, v1
	v_mov_b32_e32 v4, v1
	v_mov_b32_e32 v5, v1
	v_mov_b32_e32 v6, v1
	v_mov_b32_e32 v7, v1
	v_mov_b32_e32 v8, v1
	v_mov_b32_e32 v9, v1
	v_mov_b32_e32 v10, v1
	v_mov_b32_e32 v11, v1
	v_mov_b32_e32 v12, v1
	v_mov_b32_e32 v13, v1
	v_mov_b64_e32 v[62:63], v[14:15]
	v_mov_b64_e32 v[30:31], v[14:15]
	v_mov_b64_e32 v[78:79], v[14:15]
	v_mov_b64_e32 v[46:47], v[14:15]
	s_mov_b32 s12, 0
	v_mul_u32_u24_e32 v190, 0x58, v173
	s_add_i32 s13, s31, 1
	v_mov_b32_e32 v184, 0
	v_mov_b32_e32 v175, 0xf149f2ca
	v_mov_b64_e32 v[60:61], v[12:13]
	v_mov_b64_e32 v[58:59], v[10:11]
	v_mov_b64_e32 v[56:57], v[8:9]
	v_mov_b64_e32 v[54:55], v[6:7]
	v_mov_b64_e32 v[52:53], v[4:5]
	v_mov_b64_e32 v[50:51], v[2:3]
	v_mov_b64_e32 v[48:49], v[0:1]
	v_mov_b64_e32 v[28:29], v[12:13]
	v_mov_b64_e32 v[26:27], v[10:11]
	v_mov_b64_e32 v[24:25], v[8:9]
	v_mov_b64_e32 v[22:23], v[6:7]
	v_mov_b64_e32 v[20:21], v[4:5]
	v_mov_b64_e32 v[18:19], v[2:3]
	v_mov_b64_e32 v[16:17], v[0:1]
	v_mov_b64_e32 v[76:77], v[12:13]
	v_mov_b64_e32 v[74:75], v[10:11]
	v_mov_b64_e32 v[72:73], v[8:9]
	v_mov_b64_e32 v[70:71], v[6:7]
	v_mov_b64_e32 v[68:69], v[4:5]
	v_mov_b64_e32 v[66:67], v[2:3]
	v_mov_b64_e32 v[64:65], v[0:1]
	v_mov_b64_e32 v[44:45], v[12:13]
	v_mov_b64_e32 v[42:43], v[10:11]
	v_mov_b64_e32 v[40:41], v[8:9]
	v_mov_b64_e32 v[38:39], v[6:7]
	v_mov_b64_e32 v[36:37], v[4:5]
	v_mov_b64_e32 v[34:35], v[2:3]
	v_mov_b64_e32 v[32:33], v[0:1]
	v_mov_b32_e32 v185, 0
	v_mov_b32_e32 v175, 0
	v_mov_b32_e32 v14, 0
	v_mov_b32_e32 v212, 0xf149f2ca
	v_mov_b32_e32 v213, 0xf149f2ca
	v_mov_b32_e32 v196, 0
	v_mov_b32_e32 v197, 0
	v_mov_b32_e32 v198, 0
	v_mov_b32_e32 v199, 0
	v_mov_b32_e32 v200, 0
	v_mov_b32_e32 v201, 0
	v_mov_b32_e32 v202, 0
	v_mov_b32_e32 v203, 0
	v_mov_b32_e32 v204, 0
	v_mov_b32_e32 v205, 0
	v_mov_b32_e32 v206, 0
	v_mov_b32_e32 v207, 0
	v_mov_b32_e32 v208, 0
	v_mov_b32_e32 v209, 0
	v_mov_b32_e32 v210, 0
	v_mov_b32_e32 v211, 0
	v_mov_b32_e32 v220, 0
	v_mov_b32_e32 v221, 0
	v_mov_b32_e32 v222, 0
	v_mov_b32_e32 v223, 0
	v_mov_b32_e32 v224, 0
	v_mov_b32_e32 v225, 0
	v_mov_b32_e32 v226, 0
	v_mov_b32_e32 v227, 0
	v_mov_b32_e32 v228, 0
	v_mov_b32_e32 v229, 0
	v_mov_b32_e32 v230, 0
	v_mov_b32_e32 v231, 0
	v_mov_b32_e32 v232, 0
	v_mov_b32_e32 v233, 0
	v_mov_b32_e32 v234, 0
	v_mov_b32_e32 v235, 0
	v_lshlrev_b32_e32 v214, 1, v191
	v_add_u32_e32 v217, 0x3400, v186
	v_add_u32_e32 v219, 0x3000, v177
	v_add_u32_e32 v250, 0x3800, v177
	v_lshl_add_u32 v251, v174, 1, v188
	v_lshl_add_u32 v214, v176, 1, v214
	s_branch .LBB0_753
